# v20 + out-proj (layer 0) residual epilogue de-serialised: 7 steps of f32 residual loads kept in flight (saddr addressing, dead fragment registers as buffers) instead of a 16-step load-wait-store ladde
# speedup vs baseline: 1.0147x; 1.0031x over previous
; __device__ __forceinline__ unsigned cvt_pk_bf16(float lo, float hi) { f32x2 v = {lo, hi}; bf16x2v b = __builtin_convertvector(v, bf16x2v); return __builtin_bit_cast(unsigned, b); }
;     __device__ __forceinline__ void operator()(const f32x4 (&acc)[2][2][4][2], const Unit& u, int wr, int wc, int fr, int fq) const {
;         const int row0 = u.pm * BM + wr * 64 + fr; const int col0 = u.pn * BM + wc * 32 + 8 * fq;
; #pragma unroll
;         for (int ai = 0; ai < 2; ++ai)
; #pragma unroll
;             for (int m = 0; m < 4; ++m) { const size_t off = (size_t)(row0 + ai * HALF + m * 16) * ldc + col0;
; #pragma unroll
;                 for (int bj = 0; bj < 2; ++bj) { f32x4 r0, r1;
;                     if (RF32) { r0 = __builtin_nontemporal_load((const f32x4*)((const float*)res + off + bj * HALF)); r1 = __builtin_nontemporal_load((const f32x4*)((const float*)res + off + bj * HALF + 4)); }
;                     else { const u32x4 q = *(const u32x4*)((const bf16_t*)res + off + bj * HALF);
;                         r0 = (f32x4){__builtin_bit_cast(float, q.x << 16), __builtin_bit_cast(float, q.x & 0xffff0000u), __builtin_bit_cast(float, q.y << 16), __builtin_bit_cast(float, q.y & 0xffff0000u)};
;                         r1 = (f32x4){__builtin_bit_cast(float, q.z << 16), __builtin_bit_cast(float, q.z & 0xffff0000u), __builtin_bit_cast(float, q.w << 16), __builtin_bit_cast(float, q.w & 0xffff0000u)}; }
;                     const f32x4 v0 = r0 * alpha + acc[ai][bj][m][0], v1 = r1 * alpha + acc[ai][bj][m][1];
;                     u32x4 w; w.x = cvt_pk_bf16(v0[0], v0[1]); w.y = cvt_pk_bf16(v0[2], v0[3]); w.z = cvt_pk_bf16(v1[0], v1[1]); w.w = cvt_pk_bf16(v1[2], v1[3]);
;                     *(u32x4*)(out + off + bj * HALF) = w; }
;                 if (m & 1) asm volatile("" ::: "memory"); }
;     }
.LBB0_830:
	v_lshl_add_u32 v150, s20, 8, v153
	v_lshl_or_b32 v148, s21, 8, v154
	v_ashrrev_i32_e32 v151, 31, v150
	v_ashrrev_i32_e32 v149, 31, v148
	v_lshlrev_b64 v[146:147], 10, v[150:151]
	v_readlane_b32 s40, v251, 59
	v_lshl_add_u64 v[146:147], v[146:147], 0, v[148:149]
	v_readlane_b32 s41, v251, 60
	s_andn2_b64 vcc, exec, s[4:5]
	v_lshlrev_b32_e32 v150, 2, v146
	v_lshlrev_b32_e32 v151, 1, v146
	v_readlane_b32 s42, v251, 61
	v_readlane_b32 s43, v251, 62
	v_readlane_b32 s44, v251, 63
	v_readlane_b32 s45, v250, 0
	v_readlane_b32 s46, v250, 1
	v_readlane_b32 s47, v250, 2
	v_readlane_b32 s48, v250, 3
	v_readlane_b32 s49, v250, 4
	v_readlane_b32 s50, v250, 5
	v_readlane_b32 s51, v250, 6
	v_readlane_b32 s52, v250, 7
	v_readlane_b32 s53, v250, 8
	v_readlane_b32 s54, v250, 9
	v_readlane_b32 s55, v250, 10
	s_add_u32 s98, s40, 0x0
	s_addc_u32 s99, s41, 0
	global_load_dwordx4 v[160:163], v150, s[98:99] offset:16 nt
	global_load_dwordx4 v[164:167], v150, s[98:99] nt
	global_load_dwordx4 v[168:171], v150, s[98:99] offset:528 nt
	global_load_dwordx4 v[172:175], v150, s[98:99] offset:512 nt
	s_add_u32 s98, s40, 0x10000
	s_addc_u32 s99, s41, 0
	global_load_dwordx4 v[176:179], v150, s[98:99] offset:16 nt
	global_load_dwordx4 v[180:183], v150, s[98:99] nt
	global_load_dwordx4 v[184:187], v150, s[98:99] offset:528 nt
	global_load_dwordx4 v[188:191], v150, s[98:99] offset:512 nt
	s_add_u32 s98, s40, 0x20000
	s_addc_u32 s99, s41, 0
	global_load_dwordx4 v[192:195], v150, s[98:99] offset:16 nt
	global_load_dwordx4 v[208:211], v150, s[98:99] nt
	global_load_dwordx4 v[212:215], v150, s[98:99] offset:528 nt
	global_load_dwordx4 v[216:219], v150, s[98:99] offset:512 nt
	s_add_u32 s98, s40, 0x30000
	s_addc_u32 s99, s41, 0
	global_load_dwordx4 v[220:223], v150, s[98:99] offset:16 nt
	global_load_dwordx4 v[224:227], v150, s[98:99] nt
	s_waitcnt vmcnt(12)
	v_pk_fma_f32 v[162:163], v[162:163], s[12:13], v[124:125] op_sel_hi:[1,0,1]
	v_pk_fma_f32 v[128:129], v[166:167], s[12:13], v[128:129] op_sel_hi:[1,0,1]
	v_pk_fma_f32 v[126:127], v[164:165], s[12:13], v[126:127] op_sel_hi:[1,0,1]
	v_pk_fma_f32 v[124:125], v[160:161], s[12:13], v[122:123] op_sel_hi:[1,0,1]
	v_cvt_pk_bf16_f32 v122, v126, v127
	v_cvt_pk_bf16_f32 v123, v128, v129
	v_cvt_pk_bf16_f32 v124, v124, v125
	v_cvt_pk_bf16_f32 v125, v162, v163
	s_add_u32 s100, s80, 0x0
	s_addc_u32 s101, s81, 0
	global_store_dwordx4 v151, v[122:125], s[100:101]
	global_load_dwordx4 v[160:163], v150, s[98:99] offset:528 nt
	global_load_dwordx4 v[164:167], v150, s[98:99] offset:512 nt
	s_waitcnt vmcnt(13)
	v_pk_fma_f32 v[170:171], v[170:171], s[12:13], v[116:117] op_sel_hi:[1,0,1]
	v_pk_fma_f32 v[120:121], v[174:175], s[12:13], v[120:121] op_sel_hi:[1,0,1]
	v_pk_fma_f32 v[118:119], v[172:173], s[12:13], v[118:119] op_sel_hi:[1,0,1]
	v_pk_fma_f32 v[116:117], v[168:169], s[12:13], v[114:115] op_sel_hi:[1,0,1]
	v_cvt_pk_bf16_f32 v114, v118, v119
	v_cvt_pk_bf16_f32 v115, v120, v121
	v_cvt_pk_bf16_f32 v116, v116, v117
	v_cvt_pk_bf16_f32 v117, v170, v171
	global_store_dwordx4 v151, v[114:117], s[100:101] offset:256
	s_add_u32 s98, s40, 0x80000
	s_addc_u32 s99, s41, 0
	global_load_dwordx4 v[168:171], v150, s[98:99] offset:16 nt
	global_load_dwordx4 v[172:175], v150, s[98:99] nt
	s_waitcnt vmcnt(14)
	v_pk_fma_f32 v[178:179], v[178:179], s[12:13], v[108:109] op_sel_hi:[1,0,1]
	v_pk_fma_f32 v[112:113], v[182:183], s[12:13], v[112:113] op_sel_hi:[1,0,1]
	v_pk_fma_f32 v[110:111], v[180:181], s[12:13], v[110:111] op_sel_hi:[1,0,1]
	v_pk_fma_f32 v[108:109], v[176:177], s[12:13], v[106:107] op_sel_hi:[1,0,1]
	v_cvt_pk_bf16_f32 v106, v110, v111
	v_cvt_pk_bf16_f32 v107, v112, v113
	v_cvt_pk_bf16_f32 v108, v108, v109
	v_cvt_pk_bf16_f32 v109, v178, v179
	s_add_u32 s100, s80, 0x8000
	s_addc_u32 s101, s81, 0
	global_store_dwordx4 v151, v[106:109], s[100:101]
	global_load_dwordx4 v[176:179], v150, s[98:99] offset:528 nt
	global_load_dwordx4 v[180:183], v150, s[98:99] offset:512 nt
	s_waitcnt vmcnt(15)
	v_pk_fma_f32 v[186:187], v[186:187], s[12:13], v[100:101] op_sel_hi:[1,0,1]
	v_pk_fma_f32 v[104:105], v[190:191], s[12:13], v[104:105] op_sel_hi:[1,0,1]
	v_pk_fma_f32 v[102:103], v[188:189], s[12:13], v[102:103] op_sel_hi:[1,0,1]
	v_pk_fma_f32 v[100:101], v[184:185], s[12:13], v[98:99] op_sel_hi:[1,0,1]
	v_cvt_pk_bf16_f32 v98, v102, v103
	v_cvt_pk_bf16_f32 v99, v104, v105
	v_cvt_pk_bf16_f32 v100, v100, v101
	v_cvt_pk_bf16_f32 v101, v186, v187
	global_store_dwordx4 v151, v[98:101], s[100:101] offset:256
	s_add_u32 s98, s40, 0x90000
	s_addc_u32 s99, s41, 0
	global_load_dwordx4 v[184:187], v150, s[98:99] offset:16 nt
	global_load_dwordx4 v[188:191], v150, s[98:99] nt
	s_waitcnt vmcnt(16)
	v_pk_fma_f32 v[194:195], v[194:195], s[12:13], v[92:93] op_sel_hi:[1,0,1]
	v_pk_fma_f32 v[96:97], v[210:211], s[12:13], v[96:97] op_sel_hi:[1,0,1]
	v_pk_fma_f32 v[94:95], v[208:209], s[12:13], v[94:95] op_sel_hi:[1,0,1]
	v_pk_fma_f32 v[92:93], v[192:193], s[12:13], v[90:91] op_sel_hi:[1,0,1]
	v_cvt_pk_bf16_f32 v90, v94, v95
	v_cvt_pk_bf16_f32 v91, v96, v97
	v_cvt_pk_bf16_f32 v92, v92, v93
	v_cvt_pk_bf16_f32 v93, v194, v195
	s_add_u32 s100, s80, 0x10000
	s_addc_u32 s101, s81, 0
	global_store_dwordx4 v151, v[90:93], s[100:101]
	global_load_dwordx4 v[192:195], v150, s[98:99] offset:528 nt
	global_load_dwordx4 v[208:211], v150, s[98:99] offset:512 nt
	s_waitcnt vmcnt(17)
; __device__ __forceinline__ unsigned cvt_pk_bf16(float lo, float hi) { f32x2 v = {lo, hi}; bf16x2v b = __builtin_convertvector(v, bf16x2v); return __builtin_bit_cast(unsigned, b); }
;     __device__ __forceinline__ void operator()(const f32x4 (&acc)[2][2][4][2], const Unit& u, int wr, int wc, int fr, int fq) const {
;         const int row0 = u.pm * BM + wr * 64 + fr; const int col0 = u.pn * BM + wc * 32 + 8 * fq;
; #pragma unroll
;         for (int ai = 0; ai < 2; ++ai)
; #pragma unroll
;             for (int m = 0; m < 4; ++m) { const size_t off = (size_t)(row0 + ai * HALF + m * 16) * ldc + col0;
; #pragma unroll
;                 for (int bj = 0; bj < 2; ++bj) { f32x4 r0, r1;
;                     if (RF32) { r0 = __builtin_nontemporal_load((const f32x4*)((const float*)res + off + bj * HALF)); r1 = __builtin_nontemporal_load((const f32x4*)((const float*)res + off + bj * HALF + 4)); }
;                     else { const u32x4 q = *(const u32x4*)((const bf16_t*)res + off + bj * HALF);
;                         r0 = (f32x4){__builtin_bit_cast(float, q.x << 16), __builtin_bit_cast(float, q.x & 0xffff0000u), __builtin_bit_cast(float, q.y << 16), __builtin_bit_cast(float, q.y & 0xffff0000u)};
;                         r1 = (f32x4){__builtin_bit_cast(float, q.z << 16), __builtin_bit_cast(float, q.z & 0xffff0000u), __builtin_bit_cast(float, q.w << 16), __builtin_bit_cast(float, q.w & 0xffff0000u)}; }
;                     const f32x4 v0 = r0 * alpha + acc[ai][bj][m][0], v1 = r1 * alpha + acc[ai][bj][m][1];
;                     u32x4 w; w.x = cvt_pk_bf16(v0[0], v0[1]); w.y = cvt_pk_bf16(v0[2], v0[3]); w.z = cvt_pk_bf16(v1[0], v1[1]); w.w = cvt_pk_bf16(v1[2], v1[3]);
;                     *(u32x4*)(out + off + bj * HALF) = w; }
;                 if (m & 1) asm volatile("" ::: "memory"); }
;     }
	v_pk_fma_f32 v[214:215], v[214:215], s[12:13], v[84:85] op_sel_hi:[1,0,1]
	v_pk_fma_f32 v[88:89], v[218:219], s[12:13], v[88:89] op_sel_hi:[1,0,1]
	v_pk_fma_f32 v[86:87], v[216:217], s[12:13], v[86:87] op_sel_hi:[1,0,1]
	v_pk_fma_f32 v[84:85], v[212:213], s[12:13], v[82:83] op_sel_hi:[1,0,1]
	v_cvt_pk_bf16_f32 v82, v86, v87
	v_cvt_pk_bf16_f32 v83, v88, v89
	v_cvt_pk_bf16_f32 v84, v84, v85
	v_cvt_pk_bf16_f32 v85, v214, v215
	global_store_dwordx4 v151, v[82:85], s[100:101] offset:256
	s_add_u32 s98, s40, 0xa0000
	s_addc_u32 s99, s41, 0
	global_load_dwordx4 v[212:215], v150, s[98:99] offset:16 nt
	global_load_dwordx4 v[216:219], v150, s[98:99] nt
	s_waitcnt vmcnt(18)
	v_pk_fma_f32 v[222:223], v[222:223], s[12:13], v[76:77] op_sel_hi:[1,0,1]
	v_pk_fma_f32 v[80:81], v[226:227], s[12:13], v[80:81] op_sel_hi:[1,0,1]
	v_pk_fma_f32 v[78:79], v[224:225], s[12:13], v[78:79] op_sel_hi:[1,0,1]
	v_pk_fma_f32 v[76:77], v[220:221], s[12:13], v[74:75] op_sel_hi:[1,0,1]
	v_cvt_pk_bf16_f32 v74, v78, v79
	v_cvt_pk_bf16_f32 v75, v80, v81
	v_cvt_pk_bf16_f32 v76, v76, v77
	v_cvt_pk_bf16_f32 v77, v222, v223
	s_add_u32 s100, s80, 0x18000
	s_addc_u32 s101, s81, 0
	global_store_dwordx4 v151, v[74:77], s[100:101]
	global_load_dwordx4 v[220:223], v150, s[98:99] offset:528 nt
	global_load_dwordx4 v[224:227], v150, s[98:99] offset:512 nt
	s_waitcnt vmcnt(18)
	v_pk_fma_f32 v[162:163], v[162:163], s[12:13], v[68:69] op_sel_hi:[1,0,1]
	v_pk_fma_f32 v[72:73], v[166:167], s[12:13], v[72:73] op_sel_hi:[1,0,1]
	v_pk_fma_f32 v[70:71], v[164:165], s[12:13], v[70:71] op_sel_hi:[1,0,1]
	v_pk_fma_f32 v[68:69], v[160:161], s[12:13], v[66:67] op_sel_hi:[1,0,1]
	v_cvt_pk_bf16_f32 v66, v70, v71
	v_cvt_pk_bf16_f32 v67, v72, v73
	v_cvt_pk_bf16_f32 v68, v68, v69
	v_cvt_pk_bf16_f32 v69, v162, v163
	global_store_dwordx4 v151, v[66:69], s[100:101] offset:256
	s_add_u32 s98, s40, 0xb0000
	s_addc_u32 s99, s41, 0
	global_load_dwordx4 v[160:163], v150, s[98:99] offset:16 nt
	global_load_dwordx4 v[164:167], v150, s[98:99] nt
	s_waitcnt vmcnt(18)
	v_pk_fma_f32 v[170:171], v[170:171], s[12:13], v[60:61] op_sel_hi:[1,0,1]
	v_pk_fma_f32 v[64:65], v[174:175], s[12:13], v[64:65] op_sel_hi:[1,0,1]
	v_pk_fma_f32 v[62:63], v[172:173], s[12:13], v[62:63] op_sel_hi:[1,0,1]
	v_pk_fma_f32 v[60:61], v[168:169], s[12:13], v[58:59] op_sel_hi:[1,0,1]
	v_cvt_pk_bf16_f32 v58, v62, v63
	v_cvt_pk_bf16_f32 v59, v64, v65
	v_cvt_pk_bf16_f32 v60, v60, v61
	v_cvt_pk_bf16_f32 v61, v170, v171
	s_add_u32 s100, s80, 0x40000
	s_addc_u32 s101, s81, 0
	global_store_dwordx4 v151, v[58:61], s[100:101]
	global_load_dwordx4 v[168:171], v150, s[98:99] offset:528 nt
	global_load_dwordx4 v[172:175], v150, s[98:99] offset:512 nt
	s_waitcnt vmcnt(18)
	v_pk_fma_f32 v[178:179], v[178:179], s[12:13], v[52:53] op_sel_hi:[1,0,1]
	v_pk_fma_f32 v[56:57], v[182:183], s[12:13], v[56:57] op_sel_hi:[1,0,1]
	v_pk_fma_f32 v[54:55], v[180:181], s[12:13], v[54:55] op_sel_hi:[1,0,1]
	v_pk_fma_f32 v[52:53], v[176:177], s[12:13], v[50:51] op_sel_hi:[1,0,1]
	v_cvt_pk_bf16_f32 v50, v54, v55
	v_cvt_pk_bf16_f32 v51, v56, v57
	v_cvt_pk_bf16_f32 v52, v52, v53
	v_cvt_pk_bf16_f32 v53, v178, v179
	global_store_dwordx4 v151, v[50:53], s[100:101] offset:256
	s_waitcnt vmcnt(16)
	v_pk_fma_f32 v[186:187], v[186:187], s[12:13], v[44:45] op_sel_hi:[1,0,1]
	v_pk_fma_f32 v[48:49], v[190:191], s[12:13], v[48:49] op_sel_hi:[1,0,1]
	v_pk_fma_f32 v[46:47], v[188:189], s[12:13], v[46:47] op_sel_hi:[1,0,1]
	v_pk_fma_f32 v[44:45], v[184:185], s[12:13], v[42:43] op_sel_hi:[1,0,1]
	v_cvt_pk_bf16_f32 v42, v46, v47
	v_cvt_pk_bf16_f32 v43, v48, v49
	v_cvt_pk_bf16_f32 v44, v44, v45
	v_cvt_pk_bf16_f32 v45, v186, v187
	s_add_u32 s100, s80, 0x48000
	s_addc_u32 s101, s81, 0
	global_store_dwordx4 v151, v[42:45], s[100:101]
	s_waitcnt vmcnt(14)
	v_pk_fma_f32 v[194:195], v[194:195], s[12:13], v[36:37] op_sel_hi:[1,0,1]
	v_pk_fma_f32 v[40:41], v[210:211], s[12:13], v[40:41] op_sel_hi:[1,0,1]
	v_pk_fma_f32 v[38:39], v[208:209], s[12:13], v[38:39] op_sel_hi:[1,0,1]
	v_pk_fma_f32 v[36:37], v[192:193], s[12:13], v[34:35] op_sel_hi:[1,0,1]
	v_cvt_pk_bf16_f32 v34, v38, v39
	v_cvt_pk_bf16_f32 v35, v40, v41
	v_cvt_pk_bf16_f32 v36, v36, v37
	v_cvt_pk_bf16_f32 v37, v194, v195
	global_store_dwordx4 v151, v[34:37], s[100:101] offset:256
	s_waitcnt vmcnt(12)
	v_pk_fma_f32 v[214:215], v[214:215], s[12:13], v[28:29] op_sel_hi:[1,0,1]
	v_pk_fma_f32 v[32:33], v[218:219], s[12:13], v[32:33] op_sel_hi:[1,0,1]
	v_pk_fma_f32 v[30:31], v[216:217], s[12:13], v[30:31] op_sel_hi:[1,0,1]
	v_pk_fma_f32 v[28:29], v[212:213], s[12:13], v[26:27] op_sel_hi:[1,0,1]
	v_cvt_pk_bf16_f32 v26, v30, v31
	v_cvt_pk_bf16_f32 v27, v32, v33
	v_cvt_pk_bf16_f32 v28, v28, v29
	v_cvt_pk_bf16_f32 v29, v214, v215
	s_add_u32 s100, s80, 0x50000
	s_addc_u32 s101, s81, 0
	global_store_dwordx4 v151, v[26:29], s[100:101]
	s_waitcnt vmcnt(10)
	v_pk_fma_f32 v[222:223], v[222:223], s[12:13], v[20:21] op_sel_hi:[1,0,1]
	v_pk_fma_f32 v[24:25], v[226:227], s[12:13], v[24:25] op_sel_hi:[1,0,1]
	v_pk_fma_f32 v[22:23], v[224:225], s[12:13], v[22:23] op_sel_hi:[1,0,1]
	v_pk_fma_f32 v[20:21], v[220:221], s[12:13], v[18:19] op_sel_hi:[1,0,1]
	v_cvt_pk_bf16_f32 v18, v22, v23
	v_cvt_pk_bf16_f32 v19, v24, v25
	v_cvt_pk_bf16_f32 v20, v20, v21
	v_cvt_pk_bf16_f32 v21, v222, v223
	global_store_dwordx4 v151, v[18:21], s[100:101] offset:256
	s_waitcnt vmcnt(8)
	v_pk_fma_f32 v[162:163], v[162:163], s[12:13], v[12:13] op_sel_hi:[1,0,1]
	v_pk_fma_f32 v[16:17], v[166:167], s[12:13], v[16:17] op_sel_hi:[1,0,1]
	v_pk_fma_f32 v[14:15], v[164:165], s[12:13], v[14:15] op_sel_hi:[1,0,1]
	v_pk_fma_f32 v[12:13], v[160:161], s[12:13], v[10:11] op_sel_hi:[1,0,1]
	v_cvt_pk_bf16_f32 v10, v14, v15
	v_cvt_pk_bf16_f32 v11, v16, v17
	v_cvt_pk_bf16_f32 v12, v12, v13
	v_cvt_pk_bf16_f32 v13, v162, v163
	s_add_u32 s100, s80, 0x58000
	s_addc_u32 s101, s81, 0
	global_store_dwordx4 v151, v[10:13], s[100:101]
	s_waitcnt vmcnt(6)
	v_pk_fma_f32 v[170:171], v[170:171], s[12:13], v[4:5] op_sel_hi:[1,0,1]
	v_pk_fma_f32 v[8:9], v[174:175], s[12:13], v[8:9] op_sel_hi:[1,0,1]
	v_pk_fma_f32 v[6:7], v[172:173], s[12:13], v[6:7] op_sel_hi:[1,0,1]
	v_pk_fma_f32 v[4:5], v[168:169], s[12:13], v[2:3] op_sel_hi:[1,0,1]
	v_cvt_pk_bf16_f32 v2, v6, v7
	v_cvt_pk_bf16_f32 v3, v8, v9
	v_cvt_pk_bf16_f32 v4, v4, v5
	v_cvt_pk_bf16_f32 v5, v170, v171
	global_store_dwordx4 v151, v[2:5], s[100:101] offset:256
	s_mov_b64 s[20:21], -1
	s_cbranch_vccnz .LBB0_819
	s_andn2_b64 vcc, exec, s[6:7]
	s_cbranch_vccnz .LBB0_818
	s_barrier
	s_branch .LBB0_818

; __global__ void __launch_bounds__(512, 2) fwd(Args args) {
	.amdhsa_kernel _Z3fwd4Args
		.amdhsa_group_segment_fixed_size 256
		.amdhsa_private_segment_fixed_size 0
		.amdhsa_kernarg_size 464
		.amdhsa_user_sgpr_count 2
		.amdhsa_user_sgpr_dispatch_ptr 0
		.amdhsa_user_sgpr_queue_ptr 0
		.amdhsa_user_sgpr_kernarg_segment_ptr 1
		.amdhsa_user_sgpr_dispatch_id 0
		.amdhsa_user_sgpr_kernarg_preload_length 0
		.amdhsa_user_sgpr_kernarg_preload_offset 0
		.amdhsa_user_sgpr_private_segment_size 0
		.amdhsa_uses_dynamic_stack 0
		.amdhsa_enable_private_segment 0
		.amdhsa_system_sgpr_workgroup_id_x 1
		.amdhsa_system_sgpr_workgroup_id_y 0
		.amdhsa_system_sgpr_workgroup_id_z 0
		.amdhsa_system_sgpr_workgroup_info 0
		.amdhsa_system_vgpr_workitem_id 2
		.amdhsa_next_free_vgpr 252
		.amdhsa_next_free_sgpr 102
		.amdhsa_accum_offset 252
		.amdhsa_reserve_vcc 1
		.amdhsa_float_round_mode_32 0
		.amdhsa_float_round_mode_16_64 0
		.amdhsa_float_denorm_mode_32 3
		.amdhsa_float_denorm_mode_16_64 3
		.amdhsa_dx10_clamp 1
		.amdhsa_ieee_mode 1
		.amdhsa_fp16_overflow 0
		.amdhsa_tg_split 0
		.amdhsa_exception_fp_ieee_invalid_op 0
		.amdhsa_exception_fp_denorm_src 0
		.amdhsa_exception_fp_ieee_div_zero 0
		.amdhsa_exception_fp_ieee_overflow 0
		.amdhsa_exception_fp_ieee_underflow 0
		.amdhsa_exception_fp_ieee_inexact 0
		.amdhsa_exception_int_div_zero 0
	.end_amdhsa_kernel

amdhsa.kernels:
  - .agpr_count:     0
    .args:
      - .offset:         0
        .size:           208
        .value_kind:     by_value
      - .offset:         208
        .size:           4
        .value_kind:     hidden_block_count_x
      - .offset:         212
        .size:           4
        .value_kind:     hidden_block_count_y
      - .offset:         216
        .size:           4
        .value_kind:     hidden_block_count_z
      - .offset:         220
        .size:           2
        .value_kind:     hidden_group_size_x
      - .offset:         222
        .size:           2
        .value_kind:     hidden_group_size_y
      - .offset:         224
        .size:           2
        .value_kind:     hidden_group_size_z
      - .offset:         226
        .size:           2
        .value_kind:     hidden_remainder_x
      - .offset:         228
        .size:           2
        .value_kind:     hidden_remainder_y
      - .offset:         230
        .size:           2
        .value_kind:     hidden_remainder_z
      - .offset:         248
        .size:           8
        .value_kind:     hidden_global_offset_x
      - .offset:         256
        .size:           8
        .value_kind:     hidden_global_offset_y
      - .offset:         264
        .size:           8
        .value_kind:     hidden_global_offset_z
      - .offset:         272
        .size:           2
        .value_kind:     hidden_grid_dims
      - .offset:         296
        .size:           8
        .value_kind:     hidden_multigrid_sync_arg
      - .offset:         328
        .size:           4
        .value_kind:     hidden_dynamic_lds_size
    .group_segment_fixed_size: 256
    .kernarg_segment_align: 8
    .kernarg_segment_size: 464
    .language:       OpenCL C
    .language_version:
      - 2
      - 0
    .max_flat_workgroup_size: 512
    .name:           _Z3fwd4Args
    .private_segment_fixed_size: 0
    .sgpr_count:     108
    .sgpr_spill_count: 127
    .symbol:         _Z3fwd4Args.kd
    .uniform_work_group_size: 1
    .uses_dynamic_stack: false
    .vgpr_count:     252
    .vgpr_spill_count: 0
    .wavefront_size: 64
